# v16 + lazy-rescale GQA + generated pipelined MLA tile body + static prio for waves 4-7 in the attention phase
# speedup vs baseline: 1.0164x; 1.0028x over previous
; template <int DQ, bool NA, int NQG>
; DI void attn_wg(const half_t* Qp, const half_t* Kp, const half_t* Vp, int q0, bool active, int seg0_start, int seg0_tiles,
;                 int seg1_start, int seg1_tiles, const float* rpb_h, int rq, char* smem, int tid, f16v (&O)[2][NQG]) {
;     ...
;         for (int ks = 0; ks < NKS; ++ks) {
;           const h8 kf = *(const h8*)(ksm + (st * 32) * KSTR + ks * 16);
; #pragma unroll
;           for (int qg = 0; qg < NQG; ++qg) S[qg] = __builtin_amdgcn_mfma_f32_32x32x16_f16(kf, qf[qg][ks], S[qg], 0, 0, 0);
;         }
;         if (masked) {
;           const int cb = st * 32;
;           const int dr = krow - rq + 7;
; #pragma unroll
;           for (int qg = 0; qg < NQG; ++qg) {
;             const int qc = qg * 32 + r;
;             const int cs = min(max(qc - 8, 0), 48);
; #pragma unroll
;             for (int i = 0; i < 16; ++i) {
;               const int c = cb + (i & 3) + 8 * (i >> 2) + 4 * h;
;               const bool valid = (c >= cs) && (c < cs + 16);
;               float bias = 0.f;
;               if (valid) bias = rpb_h[dr * 31 + (c - qc + 15)] * LOG2E;
;               S[qg][i] = valid ? S[qg][i] + bias : -1e30f;
;             }
;           }
;         }
;         h4 vf[2][2][2];
; #pragma unroll
;         for (int dvt = 0; dvt < 2; ++dvt)
; #pragma unroll
;           for (int sx = 0; sx < 2; ++sx)
; #pragma unroll
;             for (int hf = 0; hf < 2; ++hf) vf[dvt][sx][hf] = *(const h4*)(vsm + (dvt * 32) * VSTR + st * 32 + sx * 16 + hf * 8);
; #pragma unroll
;         for (int qg = 0; qg < NQG; ++qg) {
;           h8 P[2];
;           float mx = S[qg][0];
; #pragma unroll
;           for (int i = 1; i < 16; ++i) mx = fmaxf(mx, S[qg][i]);
;           mx = fmaxf(mx, __shfl_xor(mx, 32));
;           if (__builtin_amdgcn_ballot_w64(mx > mrun[qg] + 8.f) != 0ull) {
;             const float mnew = fmaxf(mrun[qg], mx);
;             const float alpha = __builtin_amdgcn_exp2f(mrun[qg] - mnew);
;             lrun[qg] *= alpha;
; #pragma unroll
;             for (int dvt = 0; dvt < 2; ++dvt)
; #pragma unroll
;               for (int i = 0; i < 16; ++i) O[dvt][qg][i] *= alpha;
;             mrun[qg] = mnew;
;           }
;           const float mn = mrun[qg];
;           f2 rs2 = {0.f, 0.f};
;           const f2 mn2 = {mn, mn};
; #pragma unroll
;           for (int i = 0; i < 16; i += 2) {
.LBB0_2192:
	v_cndmask_b32_e64 v66, 0, 1, s[18:19]
	v_cmp_ne_u32_e64 s[8:9], 1, v66
	s_andn2_b64 vcc, exec, s[18:19]
	s_cbranch_vccnz .LBB0_2199
	s_bitcmp1_b32 s24, 0
	s_cselect_b32 s24, 0x5800, 0
	v_mul_u32_u24_e32 v211, 0xd0, v174
	v_add3_u32 v211, s24, v211, v180
	v_mul_u32_u24_e32 v213, 0x90, v174
	v_add3_u32 v213, s24, v213, v175
	v_add_u32_e32 v243, 0x4600, v213
	v_add_u32_e32 v213, 0x3400, v213
	ds_read_b128 v[214:217], v211 offset:0
	ds_read_b128 v[218:221], v211 offset:32
	ds_read_b128 v[248:251], v211 offset:64
	ds_read2_b64 v[158:161], v213 offset0:0 offset1:2
	ds_read2_b64 v[162:165], v213 offset0:4 offset1:6
	ds_read2_b64 v[166:169], v243 offset0:0 offset1:2
	ds_read2_b64 v[170:173], v243 offset0:4 offset1:6
	s_waitcnt lgkmcnt(6)
	v_mfma_f32_32x32x16_f16 v[82:97], v[214:217], v[98:101], 0
	ds_read_b128 v[214:217], v211 offset:96
	s_waitcnt lgkmcnt(6)
	v_mfma_f32_32x32x16_f16 v[82:97], v[218:221], v[102:105], v[82:97]
	ds_read_b128 v[218:221], v211 offset:128
	s_waitcnt lgkmcnt(6)
	v_mfma_f32_32x32x16_f16 v[82:97], v[248:251], v[106:109], v[82:97]
	ds_read_b128 v[248:251], v211 offset:160
	s_waitcnt lgkmcnt(2)
	v_mfma_f32_32x32x16_f16 v[82:97], v[214:217], v[110:113], v[82:97]
	ds_read_b128 v[214:217], v211 offset:0
	s_waitcnt lgkmcnt(2)
	v_mfma_f32_32x32x16_f16 v[82:97], v[218:221], v[114:117], v[82:97]
	ds_read_b128 v[218:221], v211 offset:32
	s_waitcnt lgkmcnt(2)
	v_mfma_f32_32x32x16_f16 v[82:97], v[248:251], v[118:121], v[82:97]
	ds_read_b128 v[248:251], v211 offset:64
	s_nop 10
	v_max3_f32 v201, v82, v83, v84
	v_max3_f32 v203, v85, v86, v87
	v_max3_f32 v201, v201, v88, v89
	v_max3_f32 v203, v203, v90, v91
	v_max3_f32 v201, v201, v92, v93
	s_waitcnt lgkmcnt(2)
	v_mfma_f32_32x32x16_f16 v[66:81], v[214:217], v[122:125], 0
	ds_read_b128 v[214:217], v211 offset:96
	v_max3_f32 v203, v203, v94, v95
	v_max3_f32 v201, v201, v96, v97
	v_max_f32_e32 v201, v201, v203
	v_mov_b32_e32 v203, v201
	s_nop 1
	v_permlane32_swap_b32_e32 v203, v201
	v_max_f32_e32 v201, v201, v203
	v_add_f32_e32 v203, 0x41000000, v210
	s_waitcnt lgkmcnt(2)
	v_mfma_f32_32x32x16_f16 v[66:81], v[218:221], v[126:129], v[66:81]
	ds_read_b128 v[218:221], v211 offset:128
	v_cmp_gt_f32_e32 vcc, v201, v203
	s_cbranch_vccnz .Lresc_mla_0
.Lcont_mla_0:
	v_pk_add_f32 v[82:83], v[82:83], v[210:211] op_sel_hi:[1,0] neg_lo:[0,1] neg_hi:[0,1]
	v_pk_add_f32 v[84:85], v[84:85], v[210:211] op_sel_hi:[1,0] neg_lo:[0,1] neg_hi:[0,1]
	v_exp_f32_e32 v82, v82
	v_exp_f32_e32 v83, v83
	s_waitcnt lgkmcnt(2)
	v_mfma_f32_32x32x16_f16 v[66:81], v[248:251], v[130:133], v[66:81]
	ds_read_b128 v[248:251], v211 offset:160
	v_pk_add_f32 v[86:87], v[86:87], v[210:211] op_sel_hi:[1,0] neg_lo:[0,1] neg_hi:[0,1]
	v_exp_f32_e32 v84, v84
	v_exp_f32_e32 v85, v85
	v_pk_add_f32 v[88:89], v[88:89], v[210:211] op_sel_hi:[1,0] neg_lo:[0,1] neg_hi:[0,1]
	v_exp_f32_e32 v86, v86
	v_exp_f32_e32 v87, v87
	v_pk_add_f32 v[90:91], v[90:91], v[210:211] op_sel_hi:[1,0] neg_lo:[0,1] neg_hi:[0,1]
	s_waitcnt lgkmcnt(2)
	v_mfma_f32_32x32x16_f16 v[66:81], v[214:217], v[134:137], v[66:81]
	ds_read_b128 v[214:217], v211 offset:6656
	v_exp_f32_e32 v88, v88
	v_exp_f32_e32 v89, v89
	v_pk_add_f32 v[92:93], v[92:93], v[210:211] op_sel_hi:[1,0] neg_lo:[0,1] neg_hi:[0,1]
	v_exp_f32_e32 v90, v90
	v_exp_f32_e32 v91, v91
	v_pk_add_f32 v[94:95], v[94:95], v[210:211] op_sel_hi:[1,0] neg_lo:[0,1] neg_hi:[0,1]
	v_exp_f32_e32 v92, v92
	s_waitcnt lgkmcnt(2)
	v_mfma_f32_32x32x16_f16 v[66:81], v[218:221], v[138:141], v[66:81]
	ds_read_b128 v[218:221], v211 offset:6688
	v_exp_f32_e32 v93, v93
	v_pk_add_f32 v[96:97], v[96:97], v[210:211] op_sel_hi:[1,0] neg_lo:[0,1] neg_hi:[0,1]
	v_exp_f32_e32 v94, v94
	v_exp_f32_e32 v95, v95
	v_exp_f32_e32 v96, v96
	v_exp_f32_e32 v97, v97
	s_waitcnt lgkmcnt(2)
	v_mfma_f32_32x32x16_f16 v[66:81], v[248:251], v[142:145], v[66:81]
	ds_read_b128 v[248:251], v211 offset:6720
	v_cvt_pk_f16_f32 v222, v82, v83
	v_cvt_pk_f16_f32 v223, v84, v85
	v_cvt_pk_f16_f32 v224, v86, v87
	v_cvt_pk_f16_f32 v225, v88, v89
	v_cvt_pk_f16_f32 v226, v90, v91
	v_cvt_pk_f16_f32 v227, v92, v93
	v_cvt_pk_f16_f32 v228, v94, v95
	v_cvt_pk_f16_f32 v229, v96, v97
	v_pk_add_f32 v[82:83], v[82:83], v[84:85]
	v_pk_add_f32 v[86:87], v[86:87], v[88:89]
	v_pk_add_f32 v[90:91], v[90:91], v[92:93]
	v_pk_add_f32 v[94:95], v[94:95], v[96:97]
	v_pk_add_f32 v[82:83], v[82:83], v[86:87]
	v_pk_add_f32 v[90:91], v[90:91], v[94:95]
	v_pk_add_f32 v[82:83], v[82:83], v[90:91]
	v_add_f32_e32 v82, v82, v83
	v_add_f32_e32 v199, v199, v82
	v_max3_f32 v201, v66, v67, v68
	v_max3_f32 v203, v69, v70, v71
	v_max3_f32 v201, v201, v72, v73
	v_max3_f32 v203, v203, v74, v75
	v_mfma_f32_32x32x16_f16 v[2:17], v[158:161], v[222:225], v[2:17]
	v_max3_f32 v201, v201, v76, v77
	v_max3_f32 v203, v203, v78, v79
	v_max3_f32 v201, v201, v80, v81
	v_max_f32_e32 v201, v201, v203
	v_mov_b32_e32 v203, v201
	s_nop 1
	v_permlane32_swap_b32_e32 v203, v201
	v_max_f32_e32 v201, v201, v203
	v_mfma_f32_32x32x16_f16 v[18:33], v[166:169], v[222:225], v[18:33]
	v_add_f32_e32 v203, 0x41000000, v212
	v_cmp_gt_f32_e32 vcc, v201, v203
	s_cbranch_vccnz .Lresc_mla_1
; template <int DQ, bool NA, int NQG>
; DI void attn_wg(const half_t* Qp, const half_t* Kp, const half_t* Vp, int q0, bool active, int seg0_start, int seg0_tiles,
;                 int seg1_start, int seg1_tiles, const float* rpb_h, int rq, char* smem, int tid, f16v (&O)[2][NQG]) {
;     ...
;         for (int ks = 0; ks < NKS; ++ks) {
;           const h8 kf = *(const h8*)(ksm + (st * 32) * KSTR + ks * 16);
; #pragma unroll
;           for (int qg = 0; qg < NQG; ++qg) S[qg] = __builtin_amdgcn_mfma_f32_32x32x16_f16(kf, qf[qg][ks], S[qg], 0, 0, 0);
;     ...
;         for (int qg = 0; qg < NQG; ++qg) {
;           h8 P[2];
;           float mx = S[qg][0];
; #pragma unroll
;           for (int i = 1; i < 16; ++i) mx = fmaxf(mx, S[qg][i]);
;           mx = fmaxf(mx, __shfl_xor(mx, 32));
;           if (__builtin_amdgcn_ballot_w64(mx > mrun[qg] + 8.f) != 0ull) {
;             const float mnew = fmaxf(mrun[qg], mx);
;             const float alpha = __builtin_amdgcn_exp2f(mrun[qg] - mnew);
;             lrun[qg] *= alpha;
; #pragma unroll
;             for (int dvt = 0; dvt < 2; ++dvt)
; #pragma unroll
;               for (int i = 0; i < 16; ++i) O[dvt][qg][i] *= alpha;
;             mrun[qg] = mnew;
;           }
;           const float mn = mrun[qg];
;           f2 rs2 = {0.f, 0.f};
;           const f2 mn2 = {mn, mn};
; #pragma unroll
;           for (int i = 0; i < 16; i += 2) {
;             const f2 s2 = {S[qg][i], S[qg][i + 1]};
;             const f2 d2 = s2 - mn2;
;             f2 p2;
;             p2.x = __builtin_amdgcn_exp2f(d2.x);
;             p2.y = __builtin_amdgcn_exp2f(d2.y);
;             if (NA) { p2.x = (s2.x <= -1e29f) ? 0.f : p2.x; p2.y = (s2.y <= -1e29f) ? 0.f : p2.y; }
;             rs2 += p2;
;             P[i >> 3][i & 7] = (half_t)p2.x;
;             P[i >> 3][(i & 7) + 1] = (half_t)p2.y;
;           }
;           lrun[qg] += rs2.x + rs2.y;
; #pragma unroll
;           for (int dvt = 0; dvt < 2; ++dvt) {
; #pragma unroll
;             for (int sx = 0; sx < 2; ++sx) {
;               const h8 va = __builtin_shufflevector(vf[dvt][sx][0], vf[dvt][sx][1], 0, 1, 2, 3, 4, 5, 6, 7);
;               O[dvt][qg] = __builtin_amdgcn_mfma_f32_32x32x16_f16(va, P[sx], O[dvt][qg], 0, 0, 0);
;             }
;           }
;         }
.Lcont_mla_1:
	v_pk_add_f32 v[66:67], v[66:67], v[212:213] op_sel_hi:[1,0] neg_lo:[0,1] neg_hi:[0,1]
	v_pk_add_f32 v[68:69], v[68:69], v[212:213] op_sel_hi:[1,0] neg_lo:[0,1] neg_hi:[0,1]
	v_exp_f32_e32 v66, v66
	v_exp_f32_e32 v67, v67
	v_pk_add_f32 v[70:71], v[70:71], v[212:213] op_sel_hi:[1,0] neg_lo:[0,1] neg_hi:[0,1]
	v_mfma_f32_32x32x16_f16 v[2:17], v[162:165], v[226:229], v[2:17]
	v_exp_f32_e32 v68, v68
	v_exp_f32_e32 v69, v69
	v_pk_add_f32 v[72:73], v[72:73], v[212:213] op_sel_hi:[1,0] neg_lo:[0,1] neg_hi:[0,1]
	v_exp_f32_e32 v70, v70
	v_exp_f32_e32 v71, v71
	v_pk_add_f32 v[74:75], v[74:75], v[212:213] op_sel_hi:[1,0] neg_lo:[0,1] neg_hi:[0,1]
	v_exp_f32_e32 v72, v72
	v_mfma_f32_32x32x16_f16 v[18:33], v[170:173], v[226:229], v[18:33]
	v_exp_f32_e32 v73, v73
	v_pk_add_f32 v[76:77], v[76:77], v[212:213] op_sel_hi:[1,0] neg_lo:[0,1] neg_hi:[0,1]
	v_exp_f32_e32 v74, v74
	v_exp_f32_e32 v75, v75
	v_pk_add_f32 v[78:79], v[78:79], v[212:213] op_sel_hi:[1,0] neg_lo:[0,1] neg_hi:[0,1]
	s_waitcnt lgkmcnt(2)
	v_mfma_f32_32x32x16_f16 v[82:97], v[214:217], v[98:101], 0
	ds_read_b128 v[214:217], v211 offset:6752
	v_exp_f32_e32 v76, v76
	v_exp_f32_e32 v77, v77
	s_waitcnt lgkmcnt(2)
	v_mfma_f32_32x32x16_f16 v[82:97], v[218:221], v[102:105], v[82:97]
	ds_read_b128 v[218:221], v211 offset:6784
	v_pk_add_f32 v[80:81], v[80:81], v[212:213] op_sel_hi:[1,0] neg_lo:[0,1] neg_hi:[0,1]
	v_exp_f32_e32 v78, v78
	s_waitcnt lgkmcnt(2)
	v_mfma_f32_32x32x16_f16 v[82:97], v[248:251], v[106:109], v[82:97]
	ds_read_b128 v[248:251], v211 offset:6816
	v_exp_f32_e32 v79, v79
	v_exp_f32_e32 v80, v80
	s_waitcnt lgkmcnt(2)
	v_mfma_f32_32x32x16_f16 v[82:97], v[214:217], v[110:113], v[82:97]
	ds_read_b128 v[214:217], v211 offset:6656
	v_exp_f32_e32 v81, v81
	v_cvt_pk_f16_f32 v222, v66, v67
	s_waitcnt lgkmcnt(2)
	v_mfma_f32_32x32x16_f16 v[82:97], v[218:221], v[114:117], v[82:97]
	ds_read_b128 v[218:221], v211 offset:6688
	v_cvt_pk_f16_f32 v223, v68, v69
	v_cvt_pk_f16_f32 v224, v70, v71
	s_waitcnt lgkmcnt(2)
	v_mfma_f32_32x32x16_f16 v[82:97], v[248:251], v[118:121], v[82:97]
	ds_read_b128 v[248:251], v211 offset:6720
	v_cvt_pk_f16_f32 v225, v72, v73
	v_cvt_pk_f16_f32 v226, v74, v75
	v_cvt_pk_f16_f32 v227, v76, v77
	v_cvt_pk_f16_f32 v228, v78, v79
	v_cvt_pk_f16_f32 v229, v80, v81
	v_pk_add_f32 v[66:67], v[66:67], v[68:69]
	v_pk_add_f32 v[70:71], v[70:71], v[72:73]
	v_pk_add_f32 v[74:75], v[74:75], v[76:77]
	v_pk_add_f32 v[78:79], v[78:79], v[80:81]
	v_pk_add_f32 v[66:67], v[66:67], v[70:71]
	v_pk_add_f32 v[74:75], v[74:75], v[78:79]
	v_pk_add_f32 v[66:67], v[66:67], v[74:75]
	v_add_f32_e32 v66, v66, v67
	v_add_f32_e32 v1, v1, v66
	v_max3_f32 v201, v82, v83, v84
	v_max3_f32 v203, v85, v86, v87
	v_max3_f32 v201, v201, v88, v89
	v_max3_f32 v203, v203, v90, v91
	v_mfma_f32_32x32x16_f16 v[34:49], v[158:161], v[222:225], v[34:49]
	v_max3_f32 v201, v201, v92, v93
	v_max3_f32 v203, v203, v94, v95
	v_max3_f32 v201, v201, v96, v97
	v_max_f32_e32 v201, v201, v203
	v_mov_b32_e32 v203, v201
	s_nop 1
	v_permlane32_swap_b32_e32 v203, v201
	v_max_f32_e32 v201, v201, v203
	v_mfma_f32_32x32x16_f16 v[50:65], v[166:169], v[222:225], v[50:65]
	v_add_f32_e32 v203, 0x41000000, v210
	v_cmp_gt_f32_e32 vcc, v201, v203
	s_cbranch_vccnz .Lresc_mla_2
.Lcont_mla_2:
	v_pk_add_f32 v[82:83], v[82:83], v[210:211] op_sel_hi:[1,0] neg_lo:[0,1] neg_hi:[0,1]
	v_pk_add_f32 v[84:85], v[84:85], v[210:211] op_sel_hi:[1,0] neg_lo:[0,1] neg_hi:[0,1]
	v_exp_f32_e32 v82, v82
	v_exp_f32_e32 v83, v83
	v_pk_add_f32 v[86:87], v[86:87], v[210:211] op_sel_hi:[1,0] neg_lo:[0,1] neg_hi:[0,1]
	v_mfma_f32_32x32x16_f16 v[34:49], v[162:165], v[226:229], v[34:49]
	v_exp_f32_e32 v84, v84
	v_exp_f32_e32 v85, v85
	v_pk_add_f32 v[88:89], v[88:89], v[210:211] op_sel_hi:[1,0] neg_lo:[0,1] neg_hi:[0,1]
	v_exp_f32_e32 v86, v86
	v_exp_f32_e32 v87, v87
	v_pk_add_f32 v[90:91], v[90:91], v[210:211] op_sel_hi:[1,0] neg_lo:[0,1] neg_hi:[0,1]
	v_exp_f32_e32 v88, v88
	v_mfma_f32_32x32x16_f16 v[50:65], v[170:173], v[226:229], v[50:65]
	ds_read2_b64 v[158:161], v213 offset0:8 offset1:10
	ds_read2_b64 v[162:165], v213 offset0:12 offset1:14
	ds_read2_b64 v[166:169], v243 offset0:8 offset1:10
	ds_read2_b64 v[170:173], v243 offset0:12 offset1:14
	v_exp_f32_e32 v89, v89
	v_pk_add_f32 v[92:93], v[92:93], v[210:211] op_sel_hi:[1,0] neg_lo:[0,1] neg_hi:[0,1]
	v_exp_f32_e32 v90, v90
	v_exp_f32_e32 v91, v91
	v_pk_add_f32 v[94:95], v[94:95], v[210:211] op_sel_hi:[1,0] neg_lo:[0,1] neg_hi:[0,1]
	s_waitcnt lgkmcnt(6)
	v_mfma_f32_32x32x16_f16 v[66:81], v[214:217], v[122:125], 0
	ds_read_b128 v[214:217], v211 offset:6752
	v_exp_f32_e32 v92, v92
	v_exp_f32_e32 v93, v93
	s_waitcnt lgkmcnt(6)
	v_mfma_f32_32x32x16_f16 v[66:81], v[218:221], v[126:129], v[66:81]
	ds_read_b128 v[218:221], v211 offset:6784
	v_pk_add_f32 v[96:97], v[96:97], v[210:211] op_sel_hi:[1,0] neg_lo:[0,1] neg_hi:[0,1]
	v_exp_f32_e32 v94, v94
	s_waitcnt lgkmcnt(6)
	v_mfma_f32_32x32x16_f16 v[66:81], v[248:251], v[130:133], v[66:81]
	ds_read_b128 v[248:251], v211 offset:6816
	v_exp_f32_e32 v95, v95
	v_exp_f32_e32 v96, v96
	s_waitcnt lgkmcnt(2)
	v_mfma_f32_32x32x16_f16 v[66:81], v[214:217], v[134:137], v[66:81]
	v_exp_f32_e32 v97, v97
	v_cvt_pk_f16_f32 v222, v82, v83
	s_waitcnt lgkmcnt(1)
	v_mfma_f32_32x32x16_f16 v[66:81], v[218:221], v[138:141], v[66:81]
	v_cvt_pk_f16_f32 v223, v84, v85
	v_cvt_pk_f16_f32 v224, v86, v87
	s_waitcnt lgkmcnt(0)
	v_mfma_f32_32x32x16_f16 v[66:81], v[248:251], v[142:145], v[66:81]
	v_cvt_pk_f16_f32 v225, v88, v89
	v_cvt_pk_f16_f32 v226, v90, v91
	v_cvt_pk_f16_f32 v227, v92, v93
	v_cvt_pk_f16_f32 v228, v94, v95
	v_cvt_pk_f16_f32 v229, v96, v97
	v_pk_add_f32 v[82:83], v[82:83], v[84:85]
	v_pk_add_f32 v[86:87], v[86:87], v[88:89]
	v_pk_add_f32 v[90:91], v[90:91], v[92:93]
	v_pk_add_f32 v[94:95], v[94:95], v[96:97]
	v_pk_add_f32 v[82:83], v[82:83], v[86:87]
	v_pk_add_f32 v[90:91], v[90:91], v[94:95]
	v_pk_add_f32 v[82:83], v[82:83], v[90:91]
	v_add_f32_e32 v82, v82, v83
	v_add_f32_e32 v199, v199, v82
	v_max3_f32 v201, v66, v67, v68
	v_max3_f32 v203, v69, v70, v71
	v_max3_f32 v201, v201, v72, v73
	v_max3_f32 v203, v203, v74, v75
	v_mfma_f32_32x32x16_f16 v[2:17], v[158:161], v[222:225], v[2:17]
	v_max3_f32 v201, v201, v76, v77
	v_max3_f32 v203, v203, v78, v79
	v_max3_f32 v201, v201, v80, v81
	v_max_f32_e32 v201, v201, v203
	v_mov_b32_e32 v203, v201
	s_nop 1
	v_permlane32_swap_b32_e32 v203, v201
	v_max_f32_e32 v201, v201, v203
	v_mfma_f32_32x32x16_f16 v[18:33], v[166:169], v[222:225], v[18:33]
	v_add_f32_e32 v203, 0x41000000, v212
	v_cmp_gt_f32_e32 vcc, v201, v203
	s_cbranch_vccnz .Lresc_mla_3
; template <int DQ, bool NA, int NQG>
; DI void attn_wg(const half_t* Qp, const half_t* Kp, const half_t* Vp, int q0, bool active, int seg0_start, int seg0_tiles,
;                 int seg1_start, int seg1_tiles, const float* rpb_h, int rq, char* smem, int tid, f16v (&O)[2][NQG]) {
;     ...
;           if (__builtin_amdgcn_ballot_w64(mx > mrun[qg] + 8.f) != 0ull) {
;             const float mnew = fmaxf(mrun[qg], mx);
;             const float alpha = __builtin_amdgcn_exp2f(mrun[qg] - mnew);
;             lrun[qg] *= alpha;
; #pragma unroll
;             for (int dvt = 0; dvt < 2; ++dvt)
; #pragma unroll
;               for (int i = 0; i < 16; ++i) O[dvt][qg][i] *= alpha;
;             mrun[qg] = mnew;
;           }
;           const float mn = mrun[qg];
;           f2 rs2 = {0.f, 0.f};
;           const f2 mn2 = {mn, mn};
; #pragma unroll
;           for (int i = 0; i < 16; i += 2) {
;             const f2 s2 = {S[qg][i], S[qg][i + 1]};
;             const f2 d2 = s2 - mn2;
;             f2 p2;
;             p2.x = __builtin_amdgcn_exp2f(d2.x);
;             p2.y = __builtin_amdgcn_exp2f(d2.y);
;             if (NA) { p2.x = (s2.x <= -1e29f) ? 0.f : p2.x; p2.y = (s2.y <= -1e29f) ? 0.f : p2.y; }
;             rs2 += p2;
;             P[i >> 3][i & 7] = (half_t)p2.x;
;             P[i >> 3][(i & 7) + 1] = (half_t)p2.y;
;           }
;           lrun[qg] += rs2.x + rs2.y;
; #pragma unroll
;           for (int dvt = 0; dvt < 2; ++dvt) {
; #pragma unroll
;             for (int sx = 0; sx < 2; ++sx) {
;               const h8 va = __builtin_shufflevector(vf[dvt][sx][0], vf[dvt][sx][1], 0, 1, 2, 3, 4, 5, 6, 7);
;               O[dvt][qg] = __builtin_amdgcn_mfma_f32_32x32x16_f16(va, P[sx], O[dvt][qg], 0, 0, 0);
;             }
;           }
;         }
.Lcont_mla_3:
	v_pk_add_f32 v[66:67], v[66:67], v[212:213] op_sel_hi:[1,0] neg_lo:[0,1] neg_hi:[0,1]
	v_pk_add_f32 v[68:69], v[68:69], v[212:213] op_sel_hi:[1,0] neg_lo:[0,1] neg_hi:[0,1]
	v_exp_f32_e32 v66, v66
	v_exp_f32_e32 v67, v67
	v_pk_add_f32 v[70:71], v[70:71], v[212:213] op_sel_hi:[1,0] neg_lo:[0,1] neg_hi:[0,1]
	v_mfma_f32_32x32x16_f16 v[2:17], v[162:165], v[226:229], v[2:17]
	v_exp_f32_e32 v68, v68
	v_exp_f32_e32 v69, v69
	v_pk_add_f32 v[72:73], v[72:73], v[212:213] op_sel_hi:[1,0] neg_lo:[0,1] neg_hi:[0,1]
	v_exp_f32_e32 v70, v70
	v_exp_f32_e32 v71, v71
	v_pk_add_f32 v[74:75], v[74:75], v[212:213] op_sel_hi:[1,0] neg_lo:[0,1] neg_hi:[0,1]
	v_exp_f32_e32 v72, v72
	v_mfma_f32_32x32x16_f16 v[18:33], v[170:173], v[226:229], v[18:33]
	v_exp_f32_e32 v73, v73
	v_pk_add_f32 v[76:77], v[76:77], v[212:213] op_sel_hi:[1,0] neg_lo:[0,1] neg_hi:[0,1]
	v_exp_f32_e32 v74, v74
	v_exp_f32_e32 v75, v75
	v_pk_add_f32 v[78:79], v[78:79], v[212:213] op_sel_hi:[1,0] neg_lo:[0,1] neg_hi:[0,1]
	v_exp_f32_e32 v76, v76
	v_exp_f32_e32 v77, v77
	v_pk_add_f32 v[80:81], v[80:81], v[212:213] op_sel_hi:[1,0] neg_lo:[0,1] neg_hi:[0,1]
	v_exp_f32_e32 v78, v78
	v_exp_f32_e32 v79, v79
	v_exp_f32_e32 v80, v80
	v_exp_f32_e32 v81, v81
	v_cvt_pk_f16_f32 v222, v66, v67
	v_cvt_pk_f16_f32 v223, v68, v69
	v_cvt_pk_f16_f32 v224, v70, v71
	v_cvt_pk_f16_f32 v225, v72, v73
	v_cvt_pk_f16_f32 v226, v74, v75
	v_cvt_pk_f16_f32 v227, v76, v77
	v_cvt_pk_f16_f32 v228, v78, v79
	v_cvt_pk_f16_f32 v229, v80, v81
	v_pk_add_f32 v[66:67], v[66:67], v[68:69]
	v_pk_add_f32 v[70:71], v[70:71], v[72:73]
	v_pk_add_f32 v[74:75], v[74:75], v[76:77]
	v_pk_add_f32 v[78:79], v[78:79], v[80:81]
	v_pk_add_f32 v[66:67], v[66:67], v[70:71]
	v_pk_add_f32 v[74:75], v[74:75], v[78:79]
	v_pk_add_f32 v[66:67], v[66:67], v[74:75]
	v_add_f32_e32 v66, v66, v67
	v_add_f32_e32 v1, v1, v66
	v_mfma_f32_32x32x16_f16 v[34:49], v[158:161], v[222:225], v[34:49]
	v_mfma_f32_32x32x16_f16 v[50:65], v[166:169], v[222:225], v[50:65]
	v_mfma_f32_32x32x16_f16 v[34:49], v[162:165], v[226:229], v[34:49]
	v_mfma_f32_32x32x16_f16 v[50:65], v[170:173], v[226:229], v[50:65]
	s_branch .Lend_mla
.Lresc_mla_0:
	s_nop 11
	v_max_f32_e32 v203, v210, v201
	v_sub_f32_e32 v246, v210, v203
	v_exp_f32_e32 v246, v246
	v_mov_b32_e32 v210, v203
	v_mul_f32_e32 v199, v199, v246
	v_pk_mul_f32 v[2:3], v[2:3], v[246:247] op_sel_hi:[1,0]
	v_pk_mul_f32 v[4:5], v[4:5], v[246:247] op_sel_hi:[1,0]
	v_pk_mul_f32 v[6:7], v[6:7], v[246:247] op_sel_hi:[1,0]
	v_pk_mul_f32 v[8:9], v[8:9], v[246:247] op_sel_hi:[1,0]
	v_pk_mul_f32 v[10:11], v[10:11], v[246:247] op_sel_hi:[1,0]
	v_pk_mul_f32 v[12:13], v[12:13], v[246:247] op_sel_hi:[1,0]
	v_pk_mul_f32 v[14:15], v[14:15], v[246:247] op_sel_hi:[1,0]
	v_pk_mul_f32 v[16:17], v[16:17], v[246:247] op_sel_hi:[1,0]
	v_pk_mul_f32 v[18:19], v[18:19], v[246:247] op_sel_hi:[1,0]
	v_pk_mul_f32 v[20:21], v[20:21], v[246:247] op_sel_hi:[1,0]
	v_pk_mul_f32 v[22:23], v[22:23], v[246:247] op_sel_hi:[1,0]
	v_pk_mul_f32 v[24:25], v[24:25], v[246:247] op_sel_hi:[1,0]
	v_pk_mul_f32 v[26:27], v[26:27], v[246:247] op_sel_hi:[1,0]
	v_pk_mul_f32 v[28:29], v[28:29], v[246:247] op_sel_hi:[1,0]
	v_pk_mul_f32 v[30:31], v[30:31], v[246:247] op_sel_hi:[1,0]
	v_pk_mul_f32 v[32:33], v[32:33], v[246:247] op_sel_hi:[1,0]
	s_branch .Lcont_mla_0
.Lresc_mla_1:
	s_nop 11
	v_max_f32_e32 v203, v212, v201
	v_sub_f32_e32 v246, v212, v203
	v_exp_f32_e32 v246, v246
	v_mov_b32_e32 v212, v203
	v_mul_f32_e32 v1, v1, v246
	v_pk_mul_f32 v[34:35], v[34:35], v[246:247] op_sel_hi:[1,0]
	v_pk_mul_f32 v[36:37], v[36:37], v[246:247] op_sel_hi:[1,0]
	v_pk_mul_f32 v[38:39], v[38:39], v[246:247] op_sel_hi:[1,0]
	v_pk_mul_f32 v[40:41], v[40:41], v[246:247] op_sel_hi:[1,0]
	v_pk_mul_f32 v[42:43], v[42:43], v[246:247] op_sel_hi:[1,0]
	v_pk_mul_f32 v[44:45], v[44:45], v[246:247] op_sel_hi:[1,0]
	v_pk_mul_f32 v[46:47], v[46:47], v[246:247] op_sel_hi:[1,0]
	v_pk_mul_f32 v[48:49], v[48:49], v[246:247] op_sel_hi:[1,0]
	v_pk_mul_f32 v[50:51], v[50:51], v[246:247] op_sel_hi:[1,0]
	v_pk_mul_f32 v[52:53], v[52:53], v[246:247] op_sel_hi:[1,0]
	v_pk_mul_f32 v[54:55], v[54:55], v[246:247] op_sel_hi:[1,0]
	v_pk_mul_f32 v[56:57], v[56:57], v[246:247] op_sel_hi:[1,0]
	v_pk_mul_f32 v[58:59], v[58:59], v[246:247] op_sel_hi:[1,0]
	v_pk_mul_f32 v[60:61], v[60:61], v[246:247] op_sel_hi:[1,0]
	v_pk_mul_f32 v[62:63], v[62:63], v[246:247] op_sel_hi:[1,0]
	v_pk_mul_f32 v[64:65], v[64:65], v[246:247] op_sel_hi:[1,0]
	s_branch .Lcont_mla_1

; template <int DQ, bool NA, int NQG>
; DI void attn_wg(const half_t* Qp, const half_t* Kp, const half_t* Vp, int q0, bool active, int seg0_start, int seg0_tiles,
;                 int seg1_start, int seg1_tiles, const float* rpb_h, int rq, char* smem, int tid, f16v (&O)[2][NQG]) {
;     ...
;     if (more) {
;       char* nb = smem + ((it + 1) & 1) * ATT_STAGE;
;       if (kc0 < KCH) *(uint4*)((half_t*)nb + ks0) = kreg0;
;       if (DQ == 96 && kc1 < KCH) *(uint4*)((half_t*)nb + ks1) = kreg1;
;       *(uint4*)((half_t*)(nb + ATT_VOFF) + vs0) = vreg;
;     }
.Lend_mla:
.LBB0_2199:
	s_andn2_b64 vcc, exec, s[20:21]
	s_cbranch_vccnz .LBB0_2205
	s_bitcmp1_b32 s28, 0
	s_cselect_b32 s24, 0x5800, 0
	s_and_saveexec_b64 s[20:21], s[4:5]
	s_cbranch_execz .LBB0_2202
	v_lshl_add_u32 v66, v197, 1, s24
	s_waitcnt vmcnt(1)
	ds_write_b128 v66, v[150:153]
